# swiglu epilogue stores with nt (streaming) hint
# baseline (speedup 1.0000x reference)
.LBB0_947:
	v_lshl_or_b32 v182, s5, 7, v190
	v_mov_b32_e32 v196, 0xbfb8aa3b
	v_mov_b32_e32 v194, 1.0
	v_lshlrev_b32_e32 v182, 1, v182
	v_pk_mul_f32 v[126:127], v[126:127], v[228:229] op_sel_hi:[1,0]
	v_pk_mul_f32 v[128:129], v[128:129], v[228:229] op_sel_hi:[1,0]
	v_pk_mul_f32 v[118:119], v[118:119], v[228:229] op_sel_hi:[1,0]
	v_pk_mul_f32 v[120:121], v[120:121], v[228:229] op_sel_hi:[1,0]
	v_pk_mul_f32 v[208:209], v[126:127], v[196:197] op_sel_hi:[1,0]
	v_pk_mul_f32 v[210:211], v[128:129], v[196:197] op_sel_hi:[1,0]
	v_pk_mul_f32 v[212:213], v[118:119], v[196:197] op_sel_hi:[1,0]
	v_pk_mul_f32 v[214:215], v[120:121], v[196:197] op_sel_hi:[1,0]
	v_pk_mul_f32 v[122:123], v[122:123], v[228:229] op_sel_hi:[1,0]
	v_pk_mul_f32 v[124:125], v[124:125], v[228:229] op_sel_hi:[1,0]
	v_pk_mul_f32 v[114:115], v[114:115], v[228:229] op_sel_hi:[1,0]
	v_pk_mul_f32 v[116:117], v[116:117], v[228:229] op_sel_hi:[1,0]
	v_exp_f32_e32 v208, v208
	v_exp_f32_e32 v209, v209
	v_exp_f32_e32 v210, v210
	v_exp_f32_e32 v211, v211
	v_exp_f32_e32 v212, v212
	v_exp_f32_e32 v213, v213
	v_exp_f32_e32 v214, v214
	v_exp_f32_e32 v215, v215
	v_pk_add_f32 v[208:209], v[208:209], v[194:195] op_sel_hi:[1,0]
	v_pk_add_f32 v[210:211], v[210:211], v[194:195] op_sel_hi:[1,0]
	v_pk_add_f32 v[212:213], v[212:213], v[194:195] op_sel_hi:[1,0]
	v_pk_add_f32 v[214:215], v[214:215], v[194:195] op_sel_hi:[1,0]
	v_rcp_f32_e32 v208, v208
	v_rcp_f32_e32 v209, v209
	v_rcp_f32_e32 v210, v210
	v_rcp_f32_e32 v211, v211
	v_rcp_f32_e32 v212, v212
	v_rcp_f32_e32 v213, v213
	v_rcp_f32_e32 v214, v214
	v_rcp_f32_e32 v215, v215
	v_pk_mul_f32 v[126:127], v[126:127], v[208:209]
	v_pk_mul_f32 v[128:129], v[128:129], v[210:211]
	v_pk_mul_f32 v[118:119], v[118:119], v[212:213]
	v_pk_mul_f32 v[120:121], v[120:121], v[214:215]
	v_pk_mul_f32 v[122:123], v[122:123], v[126:127]
	v_pk_mul_f32 v[124:125], v[124:125], v[128:129]
	v_pk_mul_f32 v[114:115], v[114:115], v[118:119]
	v_pk_mul_f32 v[116:117], v[116:117], v[120:121]
	v_cvt_pk_bf16_f32 v126, v122, v123
	v_cvt_pk_bf16_f32 v127, v124, v125
	v_cvt_pk_bf16_f32 v128, v114, v115
	v_cvt_pk_bf16_f32 v129, v116, v117
	v_mad_u32_u24 v118, v180, s31, v182
	global_store_dwordx4 v118, v[126:129], s[54:55] nt
	v_pk_mul_f32 v[110:111], v[110:111], v[230:231] op_sel_hi:[1,0]
	v_pk_mul_f32 v[112:113], v[112:113], v[230:231] op_sel_hi:[1,0]
	v_pk_mul_f32 v[102:103], v[102:103], v[230:231] op_sel_hi:[1,0]
	v_pk_mul_f32 v[104:105], v[104:105], v[230:231] op_sel_hi:[1,0]
	v_pk_mul_f32 v[216:217], v[110:111], v[196:197] op_sel_hi:[1,0]
	v_pk_mul_f32 v[218:219], v[112:113], v[196:197] op_sel_hi:[1,0]
	v_pk_mul_f32 v[220:221], v[102:103], v[196:197] op_sel_hi:[1,0]
	v_pk_mul_f32 v[222:223], v[104:105], v[196:197] op_sel_hi:[1,0]
	v_pk_mul_f32 v[106:107], v[106:107], v[230:231] op_sel_hi:[1,0]
	v_pk_mul_f32 v[108:109], v[108:109], v[230:231] op_sel_hi:[1,0]
	v_pk_mul_f32 v[98:99], v[98:99], v[230:231] op_sel_hi:[1,0]
	v_pk_mul_f32 v[100:101], v[100:101], v[230:231] op_sel_hi:[1,0]
	v_exp_f32_e32 v216, v216
	v_exp_f32_e32 v217, v217
	v_exp_f32_e32 v218, v218
	v_exp_f32_e32 v219, v219
	v_exp_f32_e32 v220, v220
	v_exp_f32_e32 v221, v221
	v_exp_f32_e32 v222, v222
	v_exp_f32_e32 v223, v223
	v_pk_add_f32 v[216:217], v[216:217], v[194:195] op_sel_hi:[1,0]
	v_pk_add_f32 v[218:219], v[218:219], v[194:195] op_sel_hi:[1,0]
	v_pk_add_f32 v[220:221], v[220:221], v[194:195] op_sel_hi:[1,0]
	v_pk_add_f32 v[222:223], v[222:223], v[194:195] op_sel_hi:[1,0]
	v_rcp_f32_e32 v216, v216
	v_rcp_f32_e32 v217, v217
	v_rcp_f32_e32 v218, v218
	v_rcp_f32_e32 v219, v219
	v_rcp_f32_e32 v220, v220
	v_rcp_f32_e32 v221, v221
	v_rcp_f32_e32 v222, v222
	v_rcp_f32_e32 v223, v223
	v_pk_mul_f32 v[110:111], v[110:111], v[216:217]
	v_pk_mul_f32 v[112:113], v[112:113], v[218:219]
	v_pk_mul_f32 v[102:103], v[102:103], v[220:221]
	v_pk_mul_f32 v[104:105], v[104:105], v[222:223]
	v_pk_mul_f32 v[106:107], v[106:107], v[110:111]
	v_pk_mul_f32 v[108:109], v[108:109], v[112:113]
	v_pk_mul_f32 v[98:99], v[98:99], v[102:103]
	v_pk_mul_f32 v[100:101], v[100:101], v[104:105]
	v_cvt_pk_bf16_f32 v110, v106, v107
	v_cvt_pk_bf16_f32 v111, v108, v109
	v_cvt_pk_bf16_f32 v112, v98, v99
	v_cvt_pk_bf16_f32 v113, v100, v101
	v_mad_u32_u24 v102, v178, s31, v182
	global_store_dwordx4 v102, v[110:113], s[54:55] nt
	v_pk_mul_f32 v[92:93], v[92:93], v[232:233] op_sel_hi:[1,0]
	v_pk_mul_f32 v[94:95], v[94:95], v[232:233] op_sel_hi:[1,0]
	v_pk_mul_f32 v[84:85], v[84:85], v[232:233] op_sel_hi:[1,0]
	v_pk_mul_f32 v[86:87], v[86:87], v[232:233] op_sel_hi:[1,0]
	v_pk_mul_f32 v[208:209], v[92:93], v[196:197] op_sel_hi:[1,0]
	v_pk_mul_f32 v[210:211], v[94:95], v[196:197] op_sel_hi:[1,0]
	v_pk_mul_f32 v[212:213], v[84:85], v[196:197] op_sel_hi:[1,0]
	v_pk_mul_f32 v[214:215], v[86:87], v[196:197] op_sel_hi:[1,0]
	v_pk_mul_f32 v[88:89], v[88:89], v[232:233] op_sel_hi:[1,0]
	v_pk_mul_f32 v[90:91], v[90:91], v[232:233] op_sel_hi:[1,0]
	v_pk_mul_f32 v[80:81], v[80:81], v[232:233] op_sel_hi:[1,0]
	v_pk_mul_f32 v[82:83], v[82:83], v[232:233] op_sel_hi:[1,0]
	v_exp_f32_e32 v208, v208
	v_exp_f32_e32 v209, v209
	v_exp_f32_e32 v210, v210
	v_exp_f32_e32 v211, v211
	v_exp_f32_e32 v212, v212
	v_exp_f32_e32 v213, v213
	v_exp_f32_e32 v214, v214
	v_exp_f32_e32 v215, v215
	v_pk_add_f32 v[208:209], v[208:209], v[194:195] op_sel_hi:[1,0]
	v_pk_add_f32 v[210:211], v[210:211], v[194:195] op_sel_hi:[1,0]
	v_pk_add_f32 v[212:213], v[212:213], v[194:195] op_sel_hi:[1,0]
	v_pk_add_f32 v[214:215], v[214:215], v[194:195] op_sel_hi:[1,0]
	v_rcp_f32_e32 v208, v208
	v_rcp_f32_e32 v209, v209
	v_rcp_f32_e32 v210, v210
	v_rcp_f32_e32 v211, v211
	v_rcp_f32_e32 v212, v212
	v_rcp_f32_e32 v213, v213
	v_rcp_f32_e32 v214, v214
	v_rcp_f32_e32 v215, v215
	v_pk_mul_f32 v[92:93], v[92:93], v[208:209]
	v_pk_mul_f32 v[94:95], v[94:95], v[210:211]
	v_pk_mul_f32 v[84:85], v[84:85], v[212:213]
	v_pk_mul_f32 v[86:87], v[86:87], v[214:215]
	v_pk_mul_f32 v[88:89], v[88:89], v[92:93]
	v_pk_mul_f32 v[90:91], v[90:91], v[94:95]
	v_pk_mul_f32 v[80:81], v[80:81], v[84:85]
	v_pk_mul_f32 v[82:83], v[82:83], v[86:87]
	v_cvt_pk_bf16_f32 v92, v88, v89
	v_cvt_pk_bf16_f32 v93, v90, v91
	v_cvt_pk_bf16_f32 v94, v80, v81
	v_cvt_pk_bf16_f32 v95, v82, v83
	v_mad_u32_u24 v84, v176, s31, v182
	global_store_dwordx4 v84, v[92:95], s[54:55] nt
	v_pk_mul_f32 v[76:77], v[76:77], v[234:235] op_sel_hi:[1,0]
	v_pk_mul_f32 v[78:79], v[78:79], v[234:235] op_sel_hi:[1,0]
	v_pk_mul_f32 v[68:69], v[68:69], v[234:235] op_sel_hi:[1,0]
	v_pk_mul_f32 v[70:71], v[70:71], v[234:235] op_sel_hi:[1,0]
	v_pk_mul_f32 v[216:217], v[76:77], v[196:197] op_sel_hi:[1,0]
	v_pk_mul_f32 v[218:219], v[78:79], v[196:197] op_sel_hi:[1,0]
	v_pk_mul_f32 v[220:221], v[68:69], v[196:197] op_sel_hi:[1,0]
	v_pk_mul_f32 v[222:223], v[70:71], v[196:197] op_sel_hi:[1,0]
	v_pk_mul_f32 v[72:73], v[72:73], v[234:235] op_sel_hi:[1,0]
	v_pk_mul_f32 v[74:75], v[74:75], v[234:235] op_sel_hi:[1,0]
	v_pk_mul_f32 v[64:65], v[64:65], v[234:235] op_sel_hi:[1,0]
	v_pk_mul_f32 v[66:67], v[66:67], v[234:235] op_sel_hi:[1,0]
	v_exp_f32_e32 v216, v216
	v_exp_f32_e32 v217, v217
	v_exp_f32_e32 v218, v218
	v_exp_f32_e32 v219, v219
	v_exp_f32_e32 v220, v220
	v_exp_f32_e32 v221, v221
	v_exp_f32_e32 v222, v222
	v_exp_f32_e32 v223, v223
	v_pk_add_f32 v[216:217], v[216:217], v[194:195] op_sel_hi:[1,0]
	v_pk_add_f32 v[218:219], v[218:219], v[194:195] op_sel_hi:[1,0]
	v_pk_add_f32 v[220:221], v[220:221], v[194:195] op_sel_hi:[1,0]
	v_pk_add_f32 v[222:223], v[222:223], v[194:195] op_sel_hi:[1,0]
	v_rcp_f32_e32 v216, v216
	v_rcp_f32_e32 v217, v217
	v_rcp_f32_e32 v218, v218
	v_rcp_f32_e32 v219, v219
	v_rcp_f32_e32 v220, v220
	v_rcp_f32_e32 v221, v221
	v_rcp_f32_e32 v222, v222
	v_rcp_f32_e32 v223, v223
	v_pk_mul_f32 v[76:77], v[76:77], v[216:217]
	v_pk_mul_f32 v[78:79], v[78:79], v[218:219]
	v_pk_mul_f32 v[68:69], v[68:69], v[220:221]
	v_pk_mul_f32 v[70:71], v[70:71], v[222:223]
	v_pk_mul_f32 v[72:73], v[72:73], v[76:77]
	v_pk_mul_f32 v[74:75], v[74:75], v[78:79]
	v_pk_mul_f32 v[64:65], v[64:65], v[68:69]
	v_pk_mul_f32 v[66:67], v[66:67], v[70:71]
	v_cvt_pk_bf16_f32 v76, v72, v73
	v_cvt_pk_bf16_f32 v77, v74, v75
	v_cvt_pk_bf16_f32 v78, v64, v65
	v_cvt_pk_bf16_f32 v79, v66, v67
	v_mad_u32_u24 v68, v174, s31, v182
	global_store_dwordx4 v68, v[76:79], s[54:55] nt
	v_pk_mul_f32 v[60:61], v[60:61], v[236:237] op_sel_hi:[1,0]
	v_pk_mul_f32 v[62:63], v[62:63], v[236:237] op_sel_hi:[1,0]
	v_pk_mul_f32 v[52:53], v[52:53], v[236:237] op_sel_hi:[1,0]
	v_pk_mul_f32 v[54:55], v[54:55], v[236:237] op_sel_hi:[1,0]
	v_pk_mul_f32 v[208:209], v[60:61], v[196:197] op_sel_hi:[1,0]
	v_pk_mul_f32 v[210:211], v[62:63], v[196:197] op_sel_hi:[1,0]
	v_pk_mul_f32 v[212:213], v[52:53], v[196:197] op_sel_hi:[1,0]
	v_pk_mul_f32 v[214:215], v[54:55], v[196:197] op_sel_hi:[1,0]
	v_pk_mul_f32 v[56:57], v[56:57], v[236:237] op_sel_hi:[1,0]
	v_pk_mul_f32 v[58:59], v[58:59], v[236:237] op_sel_hi:[1,0]
	v_pk_mul_f32 v[48:49], v[48:49], v[236:237] op_sel_hi:[1,0]
	v_pk_mul_f32 v[50:51], v[50:51], v[236:237] op_sel_hi:[1,0]
	v_exp_f32_e32 v208, v208
	v_exp_f32_e32 v209, v209
	v_exp_f32_e32 v210, v210
	v_exp_f32_e32 v211, v211
	v_exp_f32_e32 v212, v212
	v_exp_f32_e32 v213, v213
	v_exp_f32_e32 v214, v214
	v_exp_f32_e32 v215, v215
	v_pk_add_f32 v[208:209], v[208:209], v[194:195] op_sel_hi:[1,0]
	v_pk_add_f32 v[210:211], v[210:211], v[194:195] op_sel_hi:[1,0]
	v_pk_add_f32 v[212:213], v[212:213], v[194:195] op_sel_hi:[1,0]
	v_pk_add_f32 v[214:215], v[214:215], v[194:195] op_sel_hi:[1,0]
	v_rcp_f32_e32 v208, v208
	v_rcp_f32_e32 v209, v209
	v_rcp_f32_e32 v210, v210
	v_rcp_f32_e32 v211, v211
	v_rcp_f32_e32 v212, v212
	v_rcp_f32_e32 v213, v213
	v_rcp_f32_e32 v214, v214
	v_rcp_f32_e32 v215, v215
	v_pk_mul_f32 v[60:61], v[60:61], v[208:209]
	v_pk_mul_f32 v[62:63], v[62:63], v[210:211]
	v_pk_mul_f32 v[52:53], v[52:53], v[212:213]
	v_pk_mul_f32 v[54:55], v[54:55], v[214:215]
	v_pk_mul_f32 v[56:57], v[56:57], v[60:61]
	v_pk_mul_f32 v[58:59], v[58:59], v[62:63]
	v_pk_mul_f32 v[48:49], v[48:49], v[52:53]
	v_pk_mul_f32 v[50:51], v[50:51], v[54:55]
	v_cvt_pk_bf16_f32 v60, v56, v57
	v_cvt_pk_bf16_f32 v61, v58, v59
	v_cvt_pk_bf16_f32 v62, v48, v49
	v_cvt_pk_bf16_f32 v63, v50, v51
	v_mad_u32_u24 v52, v172, s31, v182
	global_store_dwordx4 v52, v[60:63], s[54:55] nt
	v_pk_mul_f32 v[44:45], v[44:45], v[238:239] op_sel_hi:[1,0]
	v_pk_mul_f32 v[46:47], v[46:47], v[238:239] op_sel_hi:[1,0]
	v_pk_mul_f32 v[36:37], v[36:37], v[238:239] op_sel_hi:[1,0]
	v_pk_mul_f32 v[38:39], v[38:39], v[238:239] op_sel_hi:[1,0]
	v_pk_mul_f32 v[216:217], v[44:45], v[196:197] op_sel_hi:[1,0]
	v_pk_mul_f32 v[218:219], v[46:47], v[196:197] op_sel_hi:[1,0]
	v_pk_mul_f32 v[220:221], v[36:37], v[196:197] op_sel_hi:[1,0]
	v_pk_mul_f32 v[222:223], v[38:39], v[196:197] op_sel_hi:[1,0]
	v_pk_mul_f32 v[40:41], v[40:41], v[238:239] op_sel_hi:[1,0]
	v_pk_mul_f32 v[42:43], v[42:43], v[238:239] op_sel_hi:[1,0]
	v_pk_mul_f32 v[32:33], v[32:33], v[238:239] op_sel_hi:[1,0]
	v_pk_mul_f32 v[34:35], v[34:35], v[238:239] op_sel_hi:[1,0]
	v_exp_f32_e32 v216, v216
	v_exp_f32_e32 v217, v217
	v_exp_f32_e32 v218, v218
	v_exp_f32_e32 v219, v219
	v_exp_f32_e32 v220, v220
	v_exp_f32_e32 v221, v221
	v_exp_f32_e32 v222, v222
	v_exp_f32_e32 v223, v223
	v_pk_add_f32 v[216:217], v[216:217], v[194:195] op_sel_hi:[1,0]
	v_pk_add_f32 v[218:219], v[218:219], v[194:195] op_sel_hi:[1,0]
	v_pk_add_f32 v[220:221], v[220:221], v[194:195] op_sel_hi:[1,0]
	v_pk_add_f32 v[222:223], v[222:223], v[194:195] op_sel_hi:[1,0]
	v_rcp_f32_e32 v216, v216
	v_rcp_f32_e32 v217, v217
	v_rcp_f32_e32 v218, v218
	v_rcp_f32_e32 v219, v219
	v_rcp_f32_e32 v220, v220
	v_rcp_f32_e32 v221, v221
	v_rcp_f32_e32 v222, v222
	v_rcp_f32_e32 v223, v223
	v_pk_mul_f32 v[44:45], v[44:45], v[216:217]
	v_pk_mul_f32 v[46:47], v[46:47], v[218:219]
	v_pk_mul_f32 v[36:37], v[36:37], v[220:221]
	v_pk_mul_f32 v[38:39], v[38:39], v[222:223]
	v_pk_mul_f32 v[40:41], v[40:41], v[44:45]
	v_pk_mul_f32 v[42:43], v[42:43], v[46:47]
	v_pk_mul_f32 v[32:33], v[32:33], v[36:37]
	v_pk_mul_f32 v[34:35], v[34:35], v[38:39]
	v_cvt_pk_bf16_f32 v44, v40, v41
	v_cvt_pk_bf16_f32 v45, v42, v43
	v_cvt_pk_bf16_f32 v46, v32, v33
	v_cvt_pk_bf16_f32 v47, v34, v35
	v_mad_u32_u24 v36, v170, s31, v182
	global_store_dwordx4 v36, v[44:47], s[54:55] nt
	v_pk_mul_f32 v[28:29], v[28:29], v[242:243] op_sel_hi:[1,0]
	v_pk_mul_f32 v[30:31], v[30:31], v[242:243] op_sel_hi:[1,0]
	v_pk_mul_f32 v[20:21], v[20:21], v[242:243] op_sel_hi:[1,0]
	v_pk_mul_f32 v[22:23], v[22:23], v[242:243] op_sel_hi:[1,0]
	v_pk_mul_f32 v[208:209], v[28:29], v[196:197] op_sel_hi:[1,0]
	v_pk_mul_f32 v[210:211], v[30:31], v[196:197] op_sel_hi:[1,0]
	v_pk_mul_f32 v[212:213], v[20:21], v[196:197] op_sel_hi:[1,0]
	v_pk_mul_f32 v[214:215], v[22:23], v[196:197] op_sel_hi:[1,0]
	v_pk_mul_f32 v[24:25], v[24:25], v[242:243] op_sel_hi:[1,0]
	v_pk_mul_f32 v[26:27], v[26:27], v[242:243] op_sel_hi:[1,0]
	v_pk_mul_f32 v[16:17], v[16:17], v[242:243] op_sel_hi:[1,0]
	v_pk_mul_f32 v[18:19], v[18:19], v[242:243] op_sel_hi:[1,0]
	v_exp_f32_e32 v208, v208
	v_exp_f32_e32 v209, v209
	v_exp_f32_e32 v210, v210
	v_exp_f32_e32 v211, v211
	v_exp_f32_e32 v212, v212
	v_exp_f32_e32 v213, v213
	v_exp_f32_e32 v214, v214
	v_exp_f32_e32 v215, v215
	v_pk_add_f32 v[208:209], v[208:209], v[194:195] op_sel_hi:[1,0]
	v_pk_add_f32 v[210:211], v[210:211], v[194:195] op_sel_hi:[1,0]
	v_pk_add_f32 v[212:213], v[212:213], v[194:195] op_sel_hi:[1,0]
	v_pk_add_f32 v[214:215], v[214:215], v[194:195] op_sel_hi:[1,0]
	v_rcp_f32_e32 v208, v208
	v_rcp_f32_e32 v209, v209
	v_rcp_f32_e32 v210, v210
	v_rcp_f32_e32 v211, v211
	v_rcp_f32_e32 v212, v212
	v_rcp_f32_e32 v213, v213
	v_rcp_f32_e32 v214, v214
	v_rcp_f32_e32 v215, v215
	v_pk_mul_f32 v[28:29], v[28:29], v[208:209]
	v_pk_mul_f32 v[30:31], v[30:31], v[210:211]
	v_pk_mul_f32 v[20:21], v[20:21], v[212:213]
	v_pk_mul_f32 v[22:23], v[22:23], v[214:215]
	v_pk_mul_f32 v[24:25], v[24:25], v[28:29]
	v_pk_mul_f32 v[26:27], v[26:27], v[30:31]
	v_pk_mul_f32 v[16:17], v[16:17], v[20:21]
	v_pk_mul_f32 v[18:19], v[18:19], v[22:23]
	v_cvt_pk_bf16_f32 v28, v24, v25
	v_cvt_pk_bf16_f32 v29, v26, v27
	v_cvt_pk_bf16_f32 v30, v16, v17
	v_cvt_pk_bf16_f32 v31, v18, v19
	v_mad_u32_u24 v20, v168, s31, v182
	global_store_dwordx4 v20, v[28:31], s[54:55] nt
	v_pk_mul_f32 v[12:13], v[12:13], v[244:245] op_sel_hi:[1,0]
	v_pk_mul_f32 v[14:15], v[14:15], v[244:245] op_sel_hi:[1,0]
	v_pk_mul_f32 v[4:5], v[4:5], v[244:245] op_sel_hi:[1,0]
	v_pk_mul_f32 v[6:7], v[6:7], v[244:245] op_sel_hi:[1,0]
	v_pk_mul_f32 v[216:217], v[12:13], v[196:197] op_sel_hi:[1,0]
	v_pk_mul_f32 v[218:219], v[14:15], v[196:197] op_sel_hi:[1,0]
	v_pk_mul_f32 v[220:221], v[4:5], v[196:197] op_sel_hi:[1,0]
	v_pk_mul_f32 v[222:223], v[6:7], v[196:197] op_sel_hi:[1,0]
	v_pk_mul_f32 v[8:9], v[8:9], v[244:245] op_sel_hi:[1,0]
	v_pk_mul_f32 v[10:11], v[10:11], v[244:245] op_sel_hi:[1,0]
	v_pk_mul_f32 v[0:1], v[0:1], v[244:245] op_sel_hi:[1,0]
	v_pk_mul_f32 v[2:3], v[2:3], v[244:245] op_sel_hi:[1,0]
	v_exp_f32_e32 v216, v216
	v_exp_f32_e32 v217, v217
	v_exp_f32_e32 v218, v218
	v_exp_f32_e32 v219, v219
	v_exp_f32_e32 v220, v220
	v_exp_f32_e32 v221, v221
	v_exp_f32_e32 v222, v222
	v_exp_f32_e32 v223, v223
	v_pk_add_f32 v[216:217], v[216:217], v[194:195] op_sel_hi:[1,0]
	v_pk_add_f32 v[218:219], v[218:219], v[194:195] op_sel_hi:[1,0]
	v_pk_add_f32 v[220:221], v[220:221], v[194:195] op_sel_hi:[1,0]
	v_pk_add_f32 v[222:223], v[222:223], v[194:195] op_sel_hi:[1,0]
	v_rcp_f32_e32 v216, v216
	v_rcp_f32_e32 v217, v217
	v_rcp_f32_e32 v218, v218
	v_rcp_f32_e32 v219, v219
	v_rcp_f32_e32 v220, v220
	v_rcp_f32_e32 v221, v221
	v_rcp_f32_e32 v222, v222
	v_rcp_f32_e32 v223, v223
	v_pk_mul_f32 v[12:13], v[12:13], v[216:217]
	v_pk_mul_f32 v[14:15], v[14:15], v[218:219]
	v_pk_mul_f32 v[4:5], v[4:5], v[220:221]
	v_pk_mul_f32 v[6:7], v[6:7], v[222:223]
	v_pk_mul_f32 v[8:9], v[8:9], v[12:13]
	v_pk_mul_f32 v[10:11], v[10:11], v[14:15]
	v_pk_mul_f32 v[0:1], v[0:1], v[4:5]
	v_pk_mul_f32 v[2:3], v[2:3], v[6:7]
	v_cvt_pk_bf16_f32 v12, v8, v9
	v_cvt_pk_bf16_f32 v13, v10, v11
	v_cvt_pk_bf16_f32 v14, v0, v1
	v_cvt_pk_bf16_f32 v15, v2, v3
	v_mad_u32_u24 v4, v166, s31, v182
	global_store_dwordx4 v4, v[12:15], s[54:55] nt
	s_waitcnt vmcnt(8)
	v_xor_b32_e32 v250, 16, v248
	v_xor_b32_e32 v251, 32, v248
	v_lshlrev_b32_e32 v250, 2, v250
	v_lshlrev_b32_e32 v251, 2, v251
	v_mov_b32_e32 v199, 0x358637bd
	v_add_f32_e32 v200, v201, v200
	v_add_f32_e32 v202, v202, v203
	v_add_f32_e32 v204, v205, v204
	v_add_f32_e32 v206, v206, v207
	v_add_f32_e32 v150, v151, v150
	v_add_f32_e32 v152, v152, v153
	v_add_f32_e32 v146, v147, v146
	v_add_f32_e32 v148, v148, v149
	v_add_f32_e32 v142, v143, v142
	v_add_f32_e32 v144, v144, v145
	v_add_f32_e32 v138, v139, v138
	v_add_f32_e32 v140, v140, v141
	v_add_f32_e32 v134, v135, v134
	v_add_f32_e32 v136, v136, v137
	v_add_f32_e32 v130, v131, v130
	v_add_f32_e32 v132, v132, v133
	v_add_f32_e32 v200, v200, v202
	v_add_f32_e32 v204, v204, v206
	v_add_f32_e32 v150, v150, v152
	v_add_f32_e32 v146, v146, v148
	v_add_f32_e32 v142, v142, v144
	v_add_f32_e32 v138, v138, v140
	v_add_f32_e32 v134, v134, v136
	v_add_f32_e32 v130, v130, v132
	ds_bpermute_b32 v201, v250, v200
	ds_bpermute_b32 v205, v250, v204
	ds_bpermute_b32 v151, v250, v150
	ds_bpermute_b32 v147, v250, v146
	ds_bpermute_b32 v143, v250, v142
	ds_bpermute_b32 v139, v250, v138
	ds_bpermute_b32 v135, v250, v134
	ds_bpermute_b32 v131, v250, v130
	s_waitcnt lgkmcnt(0)
	v_add_f32_e32 v200, v200, v201
	v_add_f32_e32 v204, v204, v205
	v_add_f32_e32 v150, v150, v151
	v_add_f32_e32 v146, v146, v147
	v_add_f32_e32 v142, v142, v143
	v_add_f32_e32 v138, v138, v139
	v_add_f32_e32 v134, v134, v135
	v_add_f32_e32 v130, v130, v131
	ds_bpermute_b32 v201, v251, v200
	ds_bpermute_b32 v205, v251, v204
	ds_bpermute_b32 v151, v251, v150
	ds_bpermute_b32 v147, v251, v146
	ds_bpermute_b32 v143, v251, v142
	ds_bpermute_b32 v139, v251, v138
	ds_bpermute_b32 v135, v251, v134
	ds_bpermute_b32 v131, v251, v130
	s_waitcnt lgkmcnt(0)
	v_add_f32_e32 v200, v200, v201
	v_add_f32_e32 v204, v204, v205
	v_add_f32_e32 v150, v150, v151
	v_add_f32_e32 v146, v146, v147
	v_add_f32_e32 v142, v142, v143
	v_add_f32_e32 v138, v138, v139
	v_add_f32_e32 v134, v134, v135
	v_add_f32_e32 v130, v130, v131
	v_fma_f32 v200, v200, s28, v199
	v_fma_f32 v204, v204, s28, v199
	v_fma_f32 v150, v150, s28, v199
	v_fma_f32 v146, v146, s28, v199
	v_fma_f32 v142, v142, s28, v199
	v_fma_f32 v138, v138, s28, v199
	v_fma_f32 v134, v134, s28, v199
	v_fma_f32 v130, v130, s28, v199
	v_rsq_f32_e32 v228, v200
	v_rsq_f32_e32 v230, v204
	v_rsq_f32_e32 v232, v150
	v_rsq_f32_e32 v234, v146
	v_rsq_f32_e32 v236, v142
	v_rsq_f32_e32 v238, v138
	v_rsq_f32_e32 v242, v134
	v_rsq_f32_e32 v244, v130
	s_andn2_b64 vcc, exec, s[0:1]
	s_mov_b64 s[4:5], -1
	s_cbranch_vccnz .LBB0_940
	s_andn2_b64 vcc, exec, s[6:7]
	s_cbranch_vccnz .LBB0_939
	s_barrier
	s_branch .LBB0_939
